# static s_setprio 1 for blocks >= 256 at every GEMM tile start (reset to 0 at MIX fetches)
# baseline (speedup 1.0000x reference)
.LBB0_96:
	s_andn2_b64 vcc, exec, s[2:3]
	s_cbranch_vccnz .LBB0_90
	v_readlane_b32 s101, v255, 14
	s_nop 0
	s_cmpk_lt_u32 s101, 0x100
	s_cbranch_scc1 .Lpr_skip0
	s_setprio 1
.Lpr_skip0:
	v_readlane_b32 s2, v253, 4
	v_readlane_b32 s3, v253, 5
	s_lshl_b32 s13, s54, 18
	s_add_u32 s2, s2, s13
	s_addc_u32 s3, s3, 0
	s_lshl_b32 s13, s56, 19
	s_add_u32 s4, s50, 0x4490000
	s_addc_u32 s5, s51, 0
	s_add_u32 s4, s4, s13
	s_addc_u32 s5, s5, 0
	v_and_b32_e32 v152, 63, v216
	v_lshrrev_b32_e32 v153, 6, v216
	v_lshrrev_b32_e32 v154, 2, v152
	v_and_b32_e32 v155, 3, v152
	v_readfirstlane_b32 s11, v153
	v_lshrrev_b32_e32 v156, 3, v154
	v_mul_u32_u24_e32 v156, 3, v156
	v_xor_b32_e32 v156, v155, v156
	v_lshlrev_b32_e32 v156, 4, v156
	v_lshl_add_u32 v157, v153, 5, v154
	v_lshl_add_u32 v203, v157, 11, v156
	v_add_u32_e32 v204, 0x8000, v203
	v_lshl_add_u32 v157, v153, 6, v154
	v_lshlrev_b32_e32 v163, 4, v152
	v_lshl_add_u32 v205, v153, 12, v163
	v_add_u32_e32 v206, 0x400, v205
	v_add_u32_e32 v207, 0x800, v205
	v_add_u32_e32 v208, 0xc00, v205
	v_and_b32_e32 v158, 15, v152
	v_lshrrev_b32_e32 v159, 4, v152
	v_lshrrev_b32_e32 v160, 3, v158
	v_mul_u32_u24_e32 v160, 3, v160
	v_xor_b32_e32 v160, v159, v160
	v_lshlrev_b32_e32 v160, 4, v160
	v_lshl_add_u32 v160, v158, 6, v160
	v_lshrrev_b32_e32 v161, 1, v153
	v_and_b32_e32 v162, 1, v153
	v_lshl_add_u32 v209, v161, 12, v160
	v_lshl_add_u32 v210, v162, 13, v160
	s_lshl_b32 s12, s11, 12
	s_lshl_b32 s11, s11, 11
	s_barrier
	s_add_u32 m0, s11, 0x0
	s_nop 0
	global_load_lds_dwordx4 v203, s[2:3]
	s_add_u32 m0, s11, 0x400
	s_nop 0
	global_load_lds_dwordx4 v204, s[2:3]
	s_add_u32 m0, s12, 0x2000
	s_nop 0
	global_load_lds_dwordx4 v205, s[4:5]
	s_add_u32 m0, s12, 0x2400
	s_nop 0
	global_load_lds_dwordx4 v206, s[4:5]
	s_add_u32 m0, s12, 0x2800
	s_nop 0
	global_load_lds_dwordx4 v207, s[4:5]
	s_add_u32 m0, s12, 0x2c00
	s_nop 0
	global_load_lds_dwordx4 v208, s[4:5]
	s_add_u32 s2, s2, 0x40
	s_addc_u32 s3, s3, 0
	s_add_u32 s4, s4, 0x4000
	s_addc_u32 s5, s5, 0
	s_add_u32 m0, s11, 0x6000
	s_nop 0
	global_load_lds_dwordx4 v203, s[2:3]
	s_add_u32 m0, s11, 0x6400
	s_nop 0
	global_load_lds_dwordx4 v204, s[2:3]
	s_add_u32 m0, s12, 0x8000
	s_nop 0
	global_load_lds_dwordx4 v205, s[4:5]
	s_add_u32 m0, s12, 0x8400
	s_nop 0
	global_load_lds_dwordx4 v206, s[4:5]
	s_add_u32 m0, s12, 0x8800
	s_nop 0
	global_load_lds_dwordx4 v207, s[4:5]
	s_add_u32 m0, s12, 0x8c00
	s_nop 0
	global_load_lds_dwordx4 v208, s[4:5]
	s_add_u32 s2, s2, 0x40
	s_addc_u32 s3, s3, 0
	s_add_u32 s4, s4, 0x4000
	s_addc_u32 s5, s5, 0
	v_mov_b32_e32 v172, 0
	v_mov_b32_e32 v173, 0
	v_mov_b32_e32 v174, 0
	v_mov_b32_e32 v175, 0
	v_mov_b32_e32 v168, 0
	v_mov_b32_e32 v169, 0
	v_mov_b32_e32 v170, 0
	v_mov_b32_e32 v171, 0
	v_mov_b32_e32 v116, 0
	v_mov_b32_e32 v117, 0
	v_mov_b32_e32 v118, 0
	v_mov_b32_e32 v119, 0
	v_mov_b32_e32 v112, 0
	v_mov_b32_e32 v113, 0
	v_mov_b32_e32 v114, 0
	v_mov_b32_e32 v115, 0
	v_mov_b32_e32 v108, 0
	v_mov_b32_e32 v109, 0
	v_mov_b32_e32 v110, 0
	v_mov_b32_e32 v111, 0
	v_mov_b32_e32 v104, 0
	v_mov_b32_e32 v105, 0
	v_mov_b32_e32 v106, 0
	v_mov_b32_e32 v107, 0
	v_mov_b32_e32 v100, 0
	v_mov_b32_e32 v101, 0
	v_mov_b32_e32 v102, 0
	v_mov_b32_e32 v103, 0
	v_mov_b32_e32 v96, 0
	v_mov_b32_e32 v97, 0
	v_mov_b32_e32 v98, 0
	v_mov_b32_e32 v99, 0
	v_mov_b32_e32 v92, 0
	v_mov_b32_e32 v93, 0
	v_mov_b32_e32 v94, 0
	v_mov_b32_e32 v95, 0
	v_mov_b32_e32 v88, 0
	v_mov_b32_e32 v89, 0
	v_mov_b32_e32 v90, 0
	v_mov_b32_e32 v91, 0
	v_mov_b32_e32 v84, 0
	v_mov_b32_e32 v85, 0
	v_mov_b32_e32 v86, 0
	v_mov_b32_e32 v87, 0
	v_mov_b32_e32 v80, 0
	v_mov_b32_e32 v81, 0
	v_mov_b32_e32 v82, 0
	v_mov_b32_e32 v83, 0
	v_mov_b32_e32 v76, 0
	v_mov_b32_e32 v77, 0
	v_mov_b32_e32 v78, 0
	v_mov_b32_e32 v79, 0
	v_mov_b32_e32 v72, 0
	v_mov_b32_e32 v73, 0
	v_mov_b32_e32 v74, 0
	v_mov_b32_e32 v75, 0
	v_mov_b32_e32 v68, 0
	v_mov_b32_e32 v69, 0
	v_mov_b32_e32 v70, 0
	v_mov_b32_e32 v71, 0
	v_mov_b32_e32 v64, 0
	v_mov_b32_e32 v65, 0
	v_mov_b32_e32 v66, 0
	v_mov_b32_e32 v67, 0
	v_mov_b32_e32 v60, 0
	v_mov_b32_e32 v61, 0
	v_mov_b32_e32 v62, 0
	v_mov_b32_e32 v63, 0
	v_mov_b32_e32 v56, 0
	v_mov_b32_e32 v57, 0
	v_mov_b32_e32 v58, 0
	v_mov_b32_e32 v59, 0
	v_mov_b32_e32 v52, 0
	v_mov_b32_e32 v53, 0
	v_mov_b32_e32 v54, 0
	v_mov_b32_e32 v55, 0
	v_mov_b32_e32 v48, 0
	v_mov_b32_e32 v49, 0
	v_mov_b32_e32 v50, 0
	v_mov_b32_e32 v51, 0
	v_mov_b32_e32 v44, 0
	v_mov_b32_e32 v45, 0
	v_mov_b32_e32 v46, 0
	v_mov_b32_e32 v47, 0
	v_mov_b32_e32 v40, 0
	v_mov_b32_e32 v41, 0
	v_mov_b32_e32 v42, 0
	v_mov_b32_e32 v43, 0
	v_mov_b32_e32 v36, 0
	v_mov_b32_e32 v37, 0
	v_mov_b32_e32 v38, 0
	v_mov_b32_e32 v39, 0
	v_mov_b32_e32 v32, 0
	v_mov_b32_e32 v33, 0
	v_mov_b32_e32 v34, 0
	v_mov_b32_e32 v35, 0
	v_mov_b32_e32 v28, 0
	v_mov_b32_e32 v29, 0
	v_mov_b32_e32 v30, 0
	v_mov_b32_e32 v31, 0
	v_mov_b32_e32 v24, 0
	v_mov_b32_e32 v25, 0
	v_mov_b32_e32 v26, 0
	v_mov_b32_e32 v27, 0
	v_mov_b32_e32 v20, 0
	v_mov_b32_e32 v21, 0
	v_mov_b32_e32 v22, 0
	v_mov_b32_e32 v23, 0
	v_mov_b32_e32 v16, 0
	v_mov_b32_e32 v17, 0
	v_mov_b32_e32 v18, 0
	v_mov_b32_e32 v19, 0
	v_mov_b32_e32 v12, 0
	v_mov_b32_e32 v13, 0
	v_mov_b32_e32 v14, 0
	v_mov_b32_e32 v15, 0
	v_mov_b32_e32 v8, 0
	v_mov_b32_e32 v9, 0
	v_mov_b32_e32 v10, 0
	v_mov_b32_e32 v11, 0
	v_mov_b32_e32 v4, 0
	v_mov_b32_e32 v5, 0
	v_mov_b32_e32 v6, 0
	v_mov_b32_e32 v7, 0
	v_mov_b32_e32 v0, 0
	v_mov_b32_e32 v1, 0
	v_mov_b32_e32 v2, 0
	v_mov_b32_e32 v3, 0
	s_waitcnt vmcnt(6)
	s_barrier
	ds_read_b128 v[120:123], v209 offset:0
	ds_read_b128 v[124:127], v209 offset:1024
	ds_read_b128 v[128:131], v209 offset:2048
	ds_read_b128 v[132:135], v209 offset:3072
	ds_read_b128 v[152:155], v210 offset:8192
	ds_read_b128 v[156:159], v210 offset:9216
	ds_read_b128 v[160:163], v210 offset:10240
	ds_read_b128 v[164:167], v210 offset:11264
	ds_read_b128 v[176:179], v210 offset:12288
	ds_read_b128 v[180:183], v210 offset:13312
	s_add_u32 m0, s11, 0xc000
	s_nop 0
	global_load_lds_dwordx4 v203, s[2:3]
	s_add_u32 m0, s11, 0xc400
	s_nop 0
	global_load_lds_dwordx4 v204, s[2:3]
	s_add_u32 m0, s12, 0xe000
	s_nop 0
	global_load_lds_dwordx4 v205, s[4:5]
	s_add_u32 m0, s12, 0xe400
	s_nop 0
	global_load_lds_dwordx4 v206, s[4:5]
	s_add_u32 m0, s12, 0xe800
	s_nop 0
	global_load_lds_dwordx4 v207, s[4:5]
	s_add_u32 m0, s12, 0xec00
	s_nop 0
	global_load_lds_dwordx4 v208, s[4:5]
	s_add_u32 s2, s2, 0x40
	s_addc_u32 s3, s3, 0
	s_add_u32 s4, s4, 0x4000
	s_addc_u32 s5, s5, 0
	ds_read_b128 v[184:187], v210 offset:14336
	ds_read_b128 v[188:191], v210 offset:15360
	s_waitcnt lgkmcnt(7)
	v_mfma_f32_16x16x32_bf16 v[172:175], v[152:155], v[120:123], v[172:175]
	v_mfma_f32_16x16x32_bf16 v[92:95], v[152:155], v[124:127], v[92:95]
	v_mfma_f32_16x16x32_bf16 v[60:63], v[152:155], v[128:131], v[60:63]
	v_mfma_f32_16x16x32_bf16 v[28:31], v[152:155], v[132:135], v[28:31]
	s_waitcnt lgkmcnt(6)
	v_mfma_f32_16x16x32_bf16 v[168:171], v[156:159], v[120:123], v[168:171]
	v_mfma_f32_16x16x32_bf16 v[88:91], v[156:159], v[124:127], v[88:91]
	v_mfma_f32_16x16x32_bf16 v[56:59], v[156:159], v[128:131], v[56:59]
	v_mfma_f32_16x16x32_bf16 v[24:27], v[156:159], v[132:135], v[24:27]
	s_waitcnt lgkmcnt(5)
	v_mfma_f32_16x16x32_bf16 v[116:119], v[160:163], v[120:123], v[116:119]
	v_mfma_f32_16x16x32_bf16 v[84:87], v[160:163], v[124:127], v[84:87]
	v_mfma_f32_16x16x32_bf16 v[52:55], v[160:163], v[128:131], v[52:55]
	v_mfma_f32_16x16x32_bf16 v[20:23], v[160:163], v[132:135], v[20:23]
	s_waitcnt lgkmcnt(4)
	v_mfma_f32_16x16x32_bf16 v[112:115], v[164:167], v[120:123], v[112:115]
	v_mfma_f32_16x16x32_bf16 v[80:83], v[164:167], v[124:127], v[80:83]
	v_mfma_f32_16x16x32_bf16 v[48:51], v[164:167], v[128:131], v[48:51]
	v_mfma_f32_16x16x32_bf16 v[16:19], v[164:167], v[132:135], v[16:19]
	s_waitcnt lgkmcnt(3)
	v_mfma_f32_16x16x32_bf16 v[108:111], v[176:179], v[120:123], v[108:111]
	v_mfma_f32_16x16x32_bf16 v[76:79], v[176:179], v[124:127], v[76:79]
	v_mfma_f32_16x16x32_bf16 v[44:47], v[176:179], v[128:131], v[44:47]
	v_mfma_f32_16x16x32_bf16 v[12:15], v[176:179], v[132:135], v[12:15]
	s_waitcnt lgkmcnt(2)
	v_mfma_f32_16x16x32_bf16 v[104:107], v[180:183], v[120:123], v[104:107]
	v_mfma_f32_16x16x32_bf16 v[72:75], v[180:183], v[124:127], v[72:75]
	v_mfma_f32_16x16x32_bf16 v[40:43], v[180:183], v[128:131], v[40:43]
	v_mfma_f32_16x16x32_bf16 v[8:11], v[180:183], v[132:135], v[8:11]
	s_waitcnt lgkmcnt(0)
	s_mov_b32 s13, 5

.Lpr_skip1:
	v_and_b32_e32 v128, 63, v216
	v_lshrrev_b32_e32 v129, 6, v216
	v_lshrrev_b32_e32 v130, 3, v128
	v_and_b32_e32 v131, 7, v128
	v_readfirstlane_b32 s12, v129
	v_lshrrev_b32_e32 v132, 1, v130
	v_lshrrev_b32_e32 v133, 2, v130
	v_xor_b32_e32 v134, v132, v133
	v_xor_b32_e32 v135, 5, v134
	v_xor_b32_e32 v134, v131, v134
	v_xor_b32_e32 v135, v131, v135
	v_lshlrev_b32_e32 v134, 4, v134
	v_lshlrev_b32_e32 v135, 4, v135
	v_lshl_add_u32 v136, v129, 5, v130
	v_mul_u32_u24_e32 v137, 0x1600, v136
	v_add_u32_e32 v192, v137, v134
	v_add_u32_e32 v193, v137, v135
	v_add_u32_e32 v193, 0xb000, v193
	v_add_u32_e32 v194, 0x16000, v192
	v_add_u32_e32 v195, 0x16000, v193
	v_and_b32_e32 v138, 15, v128
	v_lshrrev_b32_e32 v139, 4, v128
	v_lshrrev_b32_e32 v140, 1, v138
	v_lshrrev_b32_e32 v141, 2, v138
	v_lshrrev_b32_e32 v142, 3, v138
	v_xor_b32_e32 v141, v141, v142
	v_and_b32_e32 v141, 1, v141
	v_xor_b32_e32 v140, v140, v141
	v_xor_b32_e32 v140, v139, v140
	v_lshlrev_b32_e32 v140, 4, v140
	v_lshl_add_u32 v140, v138, 7, v140
	v_lshrrev_b32_e32 v141, 1, v129
	v_and_b32_e32 v142, 1, v129
	v_lshl_add_u32 v196, v141, 13, v140
	v_xor_b32_e32 v197, 64, v196
	v_lshl_add_u32 v198, v142, 13, v140
	v_xor_b32_e32 v199, 64, v198
	s_lshl_b32 s12, s12, 12
	s_mul_hi_u32 s15, s30, 0xb0000
	s_mul_i32 s14, s30, 0xb0000
	s_add_u32 s2, s28, s14
	s_addc_u32 s3, s29, s15
	s_mul_hi_u32 s15, s31, 0xb0000
	s_mul_i32 s14, s31, 0xb0000
	s_add_u32 s10, s52, s14
	s_addc_u32 s11, s53, s15
	s_add_u32 m0, s12, 0x0
	s_nop 0
	global_load_lds_dwordx4 v192, s[2:3]
	s_add_u32 m0, s12, 0x400
	s_nop 0
	global_load_lds_dwordx4 v193, s[2:3]
	s_add_u32 m0, s12, 0x800
	s_nop 0
	global_load_lds_dwordx4 v194, s[2:3]
	s_add_u32 m0, s12, 0xc00
	s_nop 0
	global_load_lds_dwordx4 v195, s[2:3]
	s_add_u32 m0, s12, 0x4000
	s_nop 0
	global_load_lds_dwordx4 v192, s[10:11]
	s_add_u32 m0, s12, 0x4400
	s_nop 0
	global_load_lds_dwordx4 v193, s[10:11]
	s_add_u32 m0, s12, 0x4800
	s_nop 0
	global_load_lds_dwordx4 v194, s[10:11]
	s_add_u32 m0, s12, 0x4c00
	s_nop 0
	global_load_lds_dwordx4 v195, s[10:11]
	s_add_u32 s2, s2, 0x80
	s_addc_u32 s3, s3, 0
	s_add_u32 s10, s10, 0x80
	s_addc_u32 s11, s11, 0
	v_mov_b32_e32 v0, 0
	v_mov_b32_e32 v1, 0
	v_mov_b32_e32 v2, 0
	v_mov_b32_e32 v3, 0
	v_mov_b32_e32 v4, 0
	v_mov_b32_e32 v5, 0
	v_mov_b32_e32 v6, 0
	v_mov_b32_e32 v7, 0
	v_mov_b32_e32 v8, 0
	v_mov_b32_e32 v9, 0
	v_mov_b32_e32 v10, 0
	v_mov_b32_e32 v11, 0
	v_mov_b32_e32 v12, 0
	v_mov_b32_e32 v13, 0
	v_mov_b32_e32 v14, 0
	v_mov_b32_e32 v15, 0
	v_mov_b32_e32 v16, 0
	v_mov_b32_e32 v17, 0
	v_mov_b32_e32 v18, 0
	v_mov_b32_e32 v19, 0
	v_mov_b32_e32 v20, 0
	v_mov_b32_e32 v21, 0
	v_mov_b32_e32 v22, 0
	v_mov_b32_e32 v23, 0
	v_mov_b32_e32 v24, 0
	v_mov_b32_e32 v25, 0
	v_mov_b32_e32 v26, 0
	v_mov_b32_e32 v27, 0
	v_mov_b32_e32 v28, 0
	v_mov_b32_e32 v29, 0
	v_mov_b32_e32 v30, 0
	v_mov_b32_e32 v31, 0
	v_mov_b32_e32 v32, 0
	v_mov_b32_e32 v33, 0
	v_mov_b32_e32 v34, 0
	v_mov_b32_e32 v35, 0
	v_mov_b32_e32 v36, 0
	v_mov_b32_e32 v37, 0
	v_mov_b32_e32 v38, 0
	v_mov_b32_e32 v39, 0
	v_mov_b32_e32 v40, 0
	v_mov_b32_e32 v41, 0
	v_mov_b32_e32 v42, 0
	v_mov_b32_e32 v43, 0
	v_mov_b32_e32 v44, 0
	v_mov_b32_e32 v45, 0
	v_mov_b32_e32 v46, 0
	v_mov_b32_e32 v47, 0
	v_mov_b32_e32 v48, 0
	v_mov_b32_e32 v49, 0
	v_mov_b32_e32 v50, 0
	v_mov_b32_e32 v51, 0
	v_mov_b32_e32 v52, 0
	v_mov_b32_e32 v53, 0
	v_mov_b32_e32 v54, 0
	v_mov_b32_e32 v55, 0
	v_mov_b32_e32 v56, 0
	v_mov_b32_e32 v57, 0
	v_mov_b32_e32 v58, 0
	v_mov_b32_e32 v59, 0
	v_mov_b32_e32 v60, 0
	v_mov_b32_e32 v61, 0
	v_mov_b32_e32 v62, 0
	v_mov_b32_e32 v63, 0
	s_waitcnt vmcnt(0)
	s_barrier
	s_add_u32 m0, s12, 0x8000
	ds_read_b128 v[64:67], v196 offset:0
	global_load_lds_dwordx4 v192, s[2:3]
	s_add_u32 m0, s12, 0x8400
	ds_read_b128 v[68:71], v196 offset:2048
	global_load_lds_dwordx4 v193, s[2:3]
	s_add_u32 m0, s12, 0x8800
	ds_read_b128 v[72:75], v196 offset:4096
	global_load_lds_dwordx4 v194, s[2:3]
	s_add_u32 m0, s12, 0x8c00
	ds_read_b128 v[76:79], v196 offset:6144
	global_load_lds_dwordx4 v195, s[2:3]
	s_add_u32 m0, s12, 0xc000
	ds_read_b128 v[96:99], v198 offset:16384
	global_load_lds_dwordx4 v192, s[10:11]
	s_add_u32 m0, s12, 0xc400
	ds_read_b128 v[100:103], v198 offset:18432
	global_load_lds_dwordx4 v193, s[10:11]
	s_add_u32 m0, s12, 0xc800
	ds_read_b128 v[104:107], v198 offset:20480
	global_load_lds_dwordx4 v194, s[10:11]
	s_add_u32 m0, s12, 0xcc00
	ds_read_b128 v[108:111], v198 offset:22528
	global_load_lds_dwordx4 v195, s[10:11]
	s_add_u32 s2, s2, 0x80
	s_addc_u32 s3, s3, 0
	s_add_u32 s10, s10, 0x80
	s_addc_u32 s11, s11, 0
	ds_read_b128 v[80:83], v197 offset:0
	ds_read_b128 v[84:87], v197 offset:2048
	ds_read_b128 v[88:91], v197 offset:4096
	ds_read_b128 v[92:95], v197 offset:6144
	ds_read_b128 v[112:115], v199 offset:16384
	ds_read_b128 v[116:119], v199 offset:18432
	ds_read_b128 v[120:123], v199 offset:20480
	ds_read_b128 v[124:127], v199 offset:22528
	s_waitcnt lgkmcnt(0)
	s_mov_b32 s13, 21

.LBB0_140:
	s_or_b64 exec, exec, s[2:3]
	s_waitcnt lgkmcnt(0)
	s_barrier
	s_waitcnt vmcnt(0)
	s_setprio 0
	ds_read_b32 v0, v201 offset:64512
	s_movk_i32 s2, 0xb27
	s_waitcnt lgkmcnt(0)
	v_cmp_lt_i32_e32 vcc, s2, v0
	v_readfirstlane_b32 s31, v0
	s_mov_b64 s[2:3], -1
	s_cbranch_vccnz .LBB0_135
	v_readlane_b32 s2, v255, 18
	v_readlane_b32 s3, v255, 19
	s_mov_b32 s92, s2
	s_cmpk_gt_i32 s31, 0x7f
	s_mov_b64 s[2:3], -1
	s_cbranch_scc0 .LBB0_445
	s_cmpk_gt_u32 s31, 0x69f
	s_cbranch_scc0 .LBB0_251
	s_cmpk_gt_u32 s31, 0x8a7
	s_cbranch_scc0 .LBB0_173
	s_cmpk_gt_u32 s31, 0x927
	s_cbranch_scc0 .LBB0_168
	v_mov_b32_e32 v40, v216
	s_lshl_b32 s4, s92, 4
	v_readfirstlane_b32 s2, v40
	s_ashr_i32 s3, s2, 6
	s_lshl_b32 s2, s31, 2
	s_and_b32 s2, s2, 12
	s_add_i32 s2, s3, s2
	s_add_i32 s4, s2, s4
	s_ashr_i32 s5, s4, 31
	v_readlane_b32 s52, v252, 16
	s_lshl_b64 s[8:9], s[4:5], 2
	v_readlane_b32 s62, v252, 26
	v_readlane_b32 s63, v252, 27
	s_add_u32 s8, s62, s8
	s_addc_u32 s9, s63, s9
	global_load_dword v4, v201, s[8:9]
	s_waitcnt vmcnt(39)
	v_and_b32_e32 v72, 63, v40
	v_lshl_or_b32 v0, s4, 6, v72
	v_ashrrev_i32_e32 v1, 31, v0
	v_readlane_b32 s60, v252, 24
	v_readlane_b32 s61, v252, 25
	v_lshlrev_b64 v[0:1], 2, v[0:1]
	v_readlane_b32 s58, v252, 22
	v_lshl_add_u64 v[2:3], s[60:61], 0, v[0:1]
	global_load_dword v37, v[2:3], off
	v_readlane_b32 s59, v252, 23
	s_mov_b32 s8, 0x3fb8aa3b
	v_readlane_b32 s53, v252, 17
	v_lshl_add_u64 v[0:1], s[58:59], 0, v[0:1]
	global_load_dword v39, v[0:1], off
	v_readlane_b32 s54, v252, 18
	v_readlane_b32 s55, v252, 19
	v_readlane_b32 s56, v252, 20
	v_readlane_b32 s57, v252, 21
	v_readlane_b32 s64, v252, 28
	v_readlane_b32 s65, v252, 29
	v_readlane_b32 s66, v252, 30
	v_readlane_b32 s67, v252, 31
	s_waitcnt vmcnt(2)
	v_mul_f32_e32 v0, 0x3fb8aa3b, v4
	v_fma_f32 v1, v4, s8, -v0
	v_rndne_f32_e32 v2, v0
	v_fmac_f32_e32 v1, 0x32a5705f, v4
	v_sub_f32_e32 v0, v0, v2
	v_add_f32_e32 v0, v0, v1
	v_cvt_i32_f32_e32 v2, v2
	v_exp_f32_e32 v0, v0
	s_mov_b32 s8, 0xc2ce8ed0
	v_cmp_ngt_f32_e32 vcc, s8, v4
	s_mov_b32 s8, 0x42b17218
	v_ldexp_f32 v0, v0, v2
	v_cndmask_b32_e32 v0, 0, v0, vcc
	v_cmp_nlt_f32_e32 vcc, s8, v4
	s_brev_b32 s8, 18
	s_nop 0
	v_cndmask_b32_e32 v41, v233, v0, vcc
	s_waitcnt vmcnt(1)
	v_mul_f32_e32 v36, v37, v41
	v_and_b32_e32 v38, 0x7fffffff, v36
	v_lshrrev_b32_e32 v0, 23, v38
	v_and_b32_e32 v2, 0x7fffff, v38
	v_cmp_nlt_f32_e64 s[14:15], |v36|, s8
	v_add_u32_e32 v1, 0xffffff88, v0
	v_or_b32_e32 v0, 0x800000, v2
	s_and_saveexec_b64 s[8:9], s[14:15]
	s_xor_b64 s[16:17], exec, s[8:9]
	s_cbranch_execz .LBB0_147
	v_cmp_lt_u32_e32 vcc, 63, v1
	s_mov_b32 s12, 0xfe5163ab
	s_nop 0
	v_cndmask_b32_e32 v2, 0, v234, vcc
	v_add_u32_e32 v2, v2, v1
	v_cmp_lt_u32_e64 s[8:9], 31, v2
	s_nop 1
	v_cndmask_b32_e64 v3, 0, v235, s[8:9]
	v_add_u32_e32 v2, v3, v2
	v_cmp_lt_u32_e64 s[10:11], 31, v2
	s_nop 1
	v_cndmask_b32_e64 v3, 0, v235, s[10:11]
	v_add_u32_e32 v16, v3, v2
	v_mad_u64_u32 v[2:3], s[12:13], v0, s12, 0
	v_mov_b32_e32 v200, v3
	s_mov_b32 s12, 0x3c439041
	v_mad_u64_u32 v[4:5], s[12:13], v0, s12, v[200:201]
	v_mov_b32_e32 v200, v5
	s_mov_b32 s12, 0xdb629599
	v_mad_u64_u32 v[6:7], s[12:13], v0, s12, v[200:201]
	v_mov_b32_e32 v200, v7
	s_mov_b32 s12, 0xf534ddc0
	v_mad_u64_u32 v[8:9], s[12:13], v0, s12, v[200:201]
	v_mov_b32_e32 v200, v9
	s_mov_b32 s12, 0xfc2757d1
	v_mad_u64_u32 v[10:11], s[12:13], v0, s12, v[200:201]
	v_mov_b32_e32 v200, v11
	s_mov_b32 s12, 0x4e441529
	v_mad_u64_u32 v[12:13], s[12:13], v0, s12, v[200:201]
	v_mov_b32_e32 v200, v13
	s_mov_b32 s12, 0xa2f9836e
	v_mad_u64_u32 v[14:15], s[12:13], v0, s12, v[200:201]
	v_cndmask_b32_e32 v3, v12, v8, vcc
	v_cndmask_b32_e32 v5, v14, v10, vcc
	v_cndmask_b32_e32 v9, v15, v12, vcc
	v_cndmask_b32_e64 v7, v5, v3, s[8:9]
	v_cndmask_b32_e64 v5, v9, v5, s[8:9]
	v_cndmask_b32_e32 v9, v10, v6, vcc
	v_cndmask_b32_e64 v3, v3, v9, s[8:9]
	v_cndmask_b32_e32 v4, v8, v4, vcc
	v_cndmask_b32_e64 v5, v5, v7, s[10:11]
	v_cndmask_b32_e64 v7, v7, v3, s[10:11]
	v_sub_u32_e32 v10, 32, v16
	v_cndmask_b32_e64 v8, v9, v4, s[8:9]
	v_alignbit_b32 v11, v5, v7, v10
	v_cmp_eq_u32_e64 s[12:13], 0, v16
	v_cndmask_b32_e64 v3, v3, v8, s[10:11]
	v_alignbit_b32 v9, v7, v3, v10
	v_cndmask_b32_e64 v5, v11, v5, s[12:13]
	v_cndmask_b32_e32 v2, v6, v2, vcc
	v_cndmask_b32_e64 v7, v9, v7, s[12:13]
	v_bfe_u32 v12, v5, 29, 1
	v_cndmask_b32_e64 v2, v4, v2, s[8:9]
	v_alignbit_b32 v9, v5, v7, 30
	v_sub_u32_e32 v13, 0, v12
	v_cndmask_b32_e64 v2, v8, v2, s[10:11]
	v_xor_b32_e32 v9, v9, v13
	v_alignbit_b32 v4, v3, v2, v10
	v_cndmask_b32_e64 v3, v4, v3, s[12:13]
	v_ffbh_u32_e32 v6, v9
	v_alignbit_b32 v4, v7, v3, 30
	v_min_u32_e32 v6, 32, v6
	v_alignbit_b32 v2, v3, v2, 30
	v_xor_b32_e32 v4, v4, v13
	v_sub_u32_e32 v7, 31, v6
	v_xor_b32_e32 v2, v2, v13
	v_alignbit_b32 v8, v9, v4, v7
	v_alignbit_b32 v2, v4, v2, v7
	v_alignbit_b32 v3, v8, v2, 9
	v_ffbh_u32_e32 v4, v3
	v_min_u32_e32 v4, 32, v4
	v_lshrrev_b32_e32 v11, 29, v5
	v_not_b32_e32 v7, v4
	v_alignbit_b32 v2, v3, v2, v7
	v_lshlrev_b32_e32 v3, 31, v11
	v_or_b32_e32 v7, 0x33000000, v3
	v_add_lshl_u32 v4, v4, v6, 23
	v_lshrrev_b32_e32 v2, 9, v2
	v_sub_u32_e32 v4, v7, v4
	v_or_b32_e32 v3, 0.5, v3
	v_lshlrev_b32_e32 v6, 23, v6
	v_or_b32_e32 v2, v4, v2
	v_lshrrev_b32_e32 v4, 9, v8
	v_sub_u32_e32 v3, v3, v6
	v_or_b32_e32 v3, v4, v3
	v_mul_f32_e32 v4, 0x3fc90fda, v3
	s_mov_b32 s8, 0x3fc90fda
	v_fma_f32 v6, v3, s8, -v4
	v_fmac_f32_e32 v6, 0x33a22168, v3
	v_fmac_f32_e32 v6, 0x3fc90fda, v2
	v_lshrrev_b32_e32 v2, 30, v5
	v_add_f32_e32 v43, v4, v6
	v_add_u32_e32 v42, v12, v2

.Lpr_skip2:
	v_readlane_b32 s11, v255, 8
	v_readlane_b32 s12, v255, 6
	v_readlane_b32 s2, v253, 4
	v_readlane_b32 s3, v253, 5
	s_lshl_b32 s13, s11, 18
	s_add_u32 s2, s2, s13
	s_addc_u32 s3, s3, 0
	s_lshl_b32 s13, s12, 19
	s_add_u32 s4, s50, 0x5510000
	s_addc_u32 s5, s51, 0
	s_add_u32 s4, s4, s13
	s_addc_u32 s5, s5, 0
	v_and_b32_e32 v92, 63, v216
	v_lshrrev_b32_e32 v93, 6, v216
	v_lshrrev_b32_e32 v94, 2, v92
	v_and_b32_e32 v95, 3, v92
	v_readfirstlane_b32 s11, v93
	v_lshrrev_b32_e32 v100, 3, v94
	v_mul_u32_u24_e32 v100, 3, v100
	v_xor_b32_e32 v100, v95, v100
	v_lshlrev_b32_e32 v100, 4, v100
	v_lshl_add_u32 v101, v93, 5, v94
	v_lshl_add_u32 v203, v101, 11, v100
	v_add_u32_e32 v204, 0x8000, v203
	v_lshl_add_u32 v101, v93, 6, v94
	v_lshlrev_b32_e32 v111, 4, v92
	v_lshl_add_u32 v205, v93, 12, v111
	v_add_u32_e32 v206, 0x400, v205
	v_add_u32_e32 v207, 0x800, v205
	v_add_u32_e32 v208, 0xc00, v205
	v_and_b32_e32 v102, 15, v92
	v_lshrrev_b32_e32 v103, 4, v92
	v_lshrrev_b32_e32 v108, 3, v102
	v_mul_u32_u24_e32 v108, 3, v108
	v_xor_b32_e32 v108, v103, v108
	v_lshlrev_b32_e32 v108, 4, v108
	v_lshl_add_u32 v108, v102, 6, v108
	v_lshrrev_b32_e32 v109, 1, v93
	v_and_b32_e32 v110, 1, v93
	v_lshl_add_u32 v209, v109, 12, v108
	v_lshl_add_u32 v210, v110, 13, v108
	s_lshl_b32 s12, s11, 12
	s_lshl_b32 s11, s11, 11
	s_barrier
	s_add_u32 m0, s11, 0x0
	s_nop 0
	global_load_lds_dwordx4 v203, s[2:3]
	s_add_u32 m0, s11, 0x400
	s_nop 0
	global_load_lds_dwordx4 v204, s[2:3]
	s_add_u32 m0, s12, 0x2000
	s_nop 0
	global_load_lds_dwordx4 v205, s[4:5]
	s_add_u32 m0, s12, 0x2400
	s_nop 0
	global_load_lds_dwordx4 v206, s[4:5]
	s_add_u32 m0, s12, 0x2800
	s_nop 0
	global_load_lds_dwordx4 v207, s[4:5]
	s_add_u32 m0, s12, 0x2c00
	s_nop 0
	global_load_lds_dwordx4 v208, s[4:5]
	s_add_u32 s2, s2, 0x40
	s_addc_u32 s3, s3, 0
	s_add_u32 s4, s4, 0x4000
	s_addc_u32 s5, s5, 0
	s_add_u32 m0, s11, 0x6000
	s_nop 0
	global_load_lds_dwordx4 v203, s[2:3]
	s_add_u32 m0, s11, 0x6400
	s_nop 0
	global_load_lds_dwordx4 v204, s[2:3]
	s_add_u32 m0, s12, 0x8000
	s_nop 0
	global_load_lds_dwordx4 v205, s[4:5]
	s_add_u32 m0, s12, 0x8400
	s_nop 0
	global_load_lds_dwordx4 v206, s[4:5]
	s_add_u32 m0, s12, 0x8800
	s_nop 0
	global_load_lds_dwordx4 v207, s[4:5]
	s_add_u32 m0, s12, 0x8c00
	s_nop 0
	global_load_lds_dwordx4 v208, s[4:5]
	s_add_u32 s2, s2, 0x40
	s_addc_u32 s3, s3, 0
	s_add_u32 s4, s4, 0x4000
	s_addc_u32 s5, s5, 0
	v_mov_b32_e32 v156, 0
	v_mov_b32_e32 v157, 0
	v_mov_b32_e32 v158, 0
	v_mov_b32_e32 v159, 0
	v_mov_b32_e32 v152, 0
	v_mov_b32_e32 v153, 0
	v_mov_b32_e32 v154, 0
	v_mov_b32_e32 v155, 0
	v_mov_b32_e32 v148, 0
	v_mov_b32_e32 v149, 0
	v_mov_b32_e32 v150, 0
	v_mov_b32_e32 v151, 0
	v_mov_b32_e32 v144, 0
	v_mov_b32_e32 v145, 0
	v_mov_b32_e32 v146, 0
	v_mov_b32_e32 v147, 0
	v_mov_b32_e32 v172, 0
	v_mov_b32_e32 v173, 0
	v_mov_b32_e32 v174, 0
	v_mov_b32_e32 v175, 0
	v_mov_b32_e32 v168, 0
	v_mov_b32_e32 v169, 0
	v_mov_b32_e32 v170, 0
	v_mov_b32_e32 v171, 0
	v_mov_b32_e32 v164, 0
	v_mov_b32_e32 v165, 0
	v_mov_b32_e32 v166, 0
	v_mov_b32_e32 v167, 0
	v_mov_b32_e32 v160, 0
	v_mov_b32_e32 v161, 0
	v_mov_b32_e32 v162, 0
	v_mov_b32_e32 v163, 0
	v_mov_b32_e32 v124, 0
	v_mov_b32_e32 v125, 0
	v_mov_b32_e32 v126, 0
	v_mov_b32_e32 v127, 0
	v_mov_b32_e32 v120, 0
	v_mov_b32_e32 v121, 0
	v_mov_b32_e32 v122, 0
	v_mov_b32_e32 v123, 0
	v_mov_b32_e32 v112, 0
	v_mov_b32_e32 v113, 0
	v_mov_b32_e32 v114, 0
	v_mov_b32_e32 v115, 0
	v_mov_b32_e32 v104, 0
	v_mov_b32_e32 v105, 0
	v_mov_b32_e32 v106, 0
	v_mov_b32_e32 v107, 0
	v_mov_b32_e32 v140, 0
	v_mov_b32_e32 v141, 0
	v_mov_b32_e32 v142, 0
	v_mov_b32_e32 v143, 0
	v_mov_b32_e32 v136, 0
	v_mov_b32_e32 v137, 0
	v_mov_b32_e32 v138, 0
	v_mov_b32_e32 v139, 0
	v_mov_b32_e32 v132, 0
	v_mov_b32_e32 v133, 0
	v_mov_b32_e32 v134, 0
	v_mov_b32_e32 v135, 0
	v_mov_b32_e32 v128, 0
	v_mov_b32_e32 v129, 0
	v_mov_b32_e32 v130, 0
	v_mov_b32_e32 v131, 0
	v_mov_b32_e32 v52, 0
	v_mov_b32_e32 v53, 0
	v_mov_b32_e32 v54, 0
	v_mov_b32_e32 v55, 0
	v_mov_b32_e32 v40, 0
	v_mov_b32_e32 v41, 0
	v_mov_b32_e32 v42, 0
	v_mov_b32_e32 v43, 0
	v_mov_b32_e32 v36, 0
	v_mov_b32_e32 v37, 0
	v_mov_b32_e32 v38, 0
	v_mov_b32_e32 v39, 0
	v_mov_b32_e32 v32, 0
	v_mov_b32_e32 v33, 0
	v_mov_b32_e32 v34, 0
	v_mov_b32_e32 v35, 0
	v_mov_b32_e32 v96, 0
	v_mov_b32_e32 v97, 0
	v_mov_b32_e32 v98, 0
	v_mov_b32_e32 v99, 0
	v_mov_b32_e32 v88, 0
	v_mov_b32_e32 v89, 0
	v_mov_b32_e32 v90, 0
	v_mov_b32_e32 v91, 0
	v_mov_b32_e32 v76, 0
	v_mov_b32_e32 v77, 0
	v_mov_b32_e32 v78, 0
	v_mov_b32_e32 v79, 0
	v_mov_b32_e32 v68, 0
	v_mov_b32_e32 v69, 0
	v_mov_b32_e32 v70, 0
	v_mov_b32_e32 v71, 0
	v_mov_b32_e32 v12, 0
	v_mov_b32_e32 v13, 0
	v_mov_b32_e32 v14, 0
	v_mov_b32_e32 v15, 0
	v_mov_b32_e32 v8, 0
	v_mov_b32_e32 v9, 0
	v_mov_b32_e32 v10, 0
	v_mov_b32_e32 v11, 0
	v_mov_b32_e32 v4, 0
	v_mov_b32_e32 v5, 0
	v_mov_b32_e32 v6, 0
	v_mov_b32_e32 v7, 0
	v_mov_b32_e32 v0, 0
	v_mov_b32_e32 v1, 0
	v_mov_b32_e32 v2, 0
	v_mov_b32_e32 v3, 0
	v_mov_b32_e32 v28, 0
	v_mov_b32_e32 v29, 0
	v_mov_b32_e32 v30, 0
	v_mov_b32_e32 v31, 0
	v_mov_b32_e32 v24, 0
	v_mov_b32_e32 v25, 0
	v_mov_b32_e32 v26, 0
	v_mov_b32_e32 v27, 0
	v_mov_b32_e32 v20, 0
	v_mov_b32_e32 v21, 0
	v_mov_b32_e32 v22, 0
	v_mov_b32_e32 v23, 0
	v_mov_b32_e32 v16, 0
	v_mov_b32_e32 v17, 0
	v_mov_b32_e32 v18, 0
	v_mov_b32_e32 v19, 0
	s_waitcnt vmcnt(6)
	s_barrier
	ds_read_b128 v[44:47], v209 offset:0
	ds_read_b128 v[48:51], v209 offset:1024
	ds_read_b128 v[56:59], v209 offset:2048
	ds_read_b128 v[60:63], v209 offset:3072
	ds_read_b128 v[92:95], v210 offset:8192
	ds_read_b128 v[100:103], v210 offset:9216
	ds_read_b128 v[108:111], v210 offset:10240
	ds_read_b128 v[116:119], v210 offset:11264
	ds_read_b128 v[176:179], v210 offset:12288
	ds_read_b128 v[180:183], v210 offset:13312
	s_add_u32 m0, s11, 0xc000
	s_nop 0
	global_load_lds_dwordx4 v203, s[2:3]
	s_add_u32 m0, s11, 0xc400
	s_nop 0
	global_load_lds_dwordx4 v204, s[2:3]
	s_add_u32 m0, s12, 0xe000
	s_nop 0
	global_load_lds_dwordx4 v205, s[4:5]
	s_add_u32 m0, s12, 0xe400
	s_nop 0
	global_load_lds_dwordx4 v206, s[4:5]
	s_add_u32 m0, s12, 0xe800
	s_nop 0
	global_load_lds_dwordx4 v207, s[4:5]
	s_add_u32 m0, s12, 0xec00
	s_nop 0
	global_load_lds_dwordx4 v208, s[4:5]
	s_add_u32 s2, s2, 0x40
	s_addc_u32 s3, s3, 0
	s_add_u32 s4, s4, 0x4000
	s_addc_u32 s5, s5, 0
	ds_read_b128 v[184:187], v210 offset:14336
	ds_read_b128 v[188:191], v210 offset:15360
	s_waitcnt lgkmcnt(7)
	v_mfma_f32_16x16x32_bf16 v[156:159], v[92:95], v[44:47], v[156:159]
	v_mfma_f32_16x16x32_bf16 v[124:127], v[92:95], v[48:51], v[124:127]
	v_mfma_f32_16x16x32_bf16 v[52:55], v[92:95], v[56:59], v[52:55]
	v_mfma_f32_16x16x32_bf16 v[12:15], v[92:95], v[60:63], v[12:15]
	s_waitcnt lgkmcnt(6)
	v_mfma_f32_16x16x32_bf16 v[152:155], v[100:103], v[44:47], v[152:155]
	v_mfma_f32_16x16x32_bf16 v[120:123], v[100:103], v[48:51], v[120:123]
	v_mfma_f32_16x16x32_bf16 v[40:43], v[100:103], v[56:59], v[40:43]
	v_mfma_f32_16x16x32_bf16 v[8:11], v[100:103], v[60:63], v[8:11]
	s_waitcnt lgkmcnt(5)
	v_mfma_f32_16x16x32_bf16 v[148:151], v[108:111], v[44:47], v[148:151]
	v_mfma_f32_16x16x32_bf16 v[112:115], v[108:111], v[48:51], v[112:115]
	v_mfma_f32_16x16x32_bf16 v[36:39], v[108:111], v[56:59], v[36:39]
	v_mfma_f32_16x16x32_bf16 v[4:7], v[108:111], v[60:63], v[4:7]
	s_waitcnt lgkmcnt(4)
	v_mfma_f32_16x16x32_bf16 v[144:147], v[116:119], v[44:47], v[144:147]
	v_mfma_f32_16x16x32_bf16 v[104:107], v[116:119], v[48:51], v[104:107]
	v_mfma_f32_16x16x32_bf16 v[32:35], v[116:119], v[56:59], v[32:35]
	v_mfma_f32_16x16x32_bf16 v[0:3], v[116:119], v[60:63], v[0:3]
	s_waitcnt lgkmcnt(3)
	v_mfma_f32_16x16x32_bf16 v[172:175], v[176:179], v[44:47], v[172:175]
	v_mfma_f32_16x16x32_bf16 v[140:143], v[176:179], v[48:51], v[140:143]
	v_mfma_f32_16x16x32_bf16 v[96:99], v[176:179], v[56:59], v[96:99]
	v_mfma_f32_16x16x32_bf16 v[28:31], v[176:179], v[60:63], v[28:31]
	s_waitcnt lgkmcnt(2)
	v_mfma_f32_16x16x32_bf16 v[168:171], v[180:183], v[44:47], v[168:171]
	v_mfma_f32_16x16x32_bf16 v[136:139], v[180:183], v[48:51], v[136:139]
	v_mfma_f32_16x16x32_bf16 v[88:91], v[180:183], v[56:59], v[88:91]
	v_mfma_f32_16x16x32_bf16 v[24:27], v[180:183], v[60:63], v[24:27]
	s_waitcnt lgkmcnt(0)
	s_mov_b32 s13, 5

.Lpr_skip3:
	v_readlane_b32 s20, v255, 4
	v_readlane_b32 s21, v255, 30
	v_and_b32_e32 v144, 63, v216
	v_lshrrev_b32_e32 v145, 6, v216
	v_lshrrev_b32_e32 v146, 3, v144
	v_and_b32_e32 v147, 7, v144
	v_readfirstlane_b32 s12, v145
	v_lshrrev_b32_e32 v148, 1, v146
	v_lshrrev_b32_e32 v149, 2, v146
	v_xor_b32_e32 v150, v148, v149
	v_xor_b32_e32 v151, 5, v150
	v_xor_b32_e32 v150, v147, v150
	v_xor_b32_e32 v151, v147, v151
	v_lshlrev_b32_e32 v150, 4, v150
	v_lshlrev_b32_e32 v151, 4, v151
	v_lshl_add_u32 v152, v145, 5, v146
	v_lshlrev_b32_e32 v153, 11, v152
	v_add_u32_e32 v192, v153, v150
	v_add_u32_e32 v193, v153, v151
	v_add_u32_e32 v193, 0x4000, v193
	v_add_u32_e32 v194, 0x8000, v192
	v_add_u32_e32 v195, 0x8000, v193
	v_lshl_add_u32 v152, v145, 4, v146
	v_lshlrev_b32_e32 v153, 11, v152
	v_add_u32_e32 v196, v153, v150
	v_add_u32_e32 v197, v153, v151
	v_add_u32_e32 v197, 0x4000, v197
	v_lshlrev_b32_e32 v153, 9, v152
	v_add_u32_e32 v198, v153, v150
	v_add_u32_e32 v199, v153, v151
	v_add_u32_e32 v199, 0x1000, v199
	v_and_b32_e32 v154, 15, v144
	v_lshrrev_b32_e32 v155, 4, v144
	v_lshrrev_b32_e32 v156, 1, v154
	v_lshrrev_b32_e32 v157, 2, v154
	v_lshrrev_b32_e32 v158, 3, v154
	v_xor_b32_e32 v157, v157, v158
	v_and_b32_e32 v157, 1, v157
	v_xor_b32_e32 v156, v156, v157
	v_xor_b32_e32 v156, v155, v156
	v_lshlrev_b32_e32 v156, 4, v156
	v_lshl_add_u32 v156, v154, 7, v156
	v_lshrrev_b32_e32 v157, 1, v145
	v_and_b32_e32 v158, 1, v145
	v_lshl_add_u32 v203, v157, 13, v156
	v_xor_b32_e32 v204, 64, v203
	v_lshl_add_u32 v205, v158, 12, v156
	v_xor_b32_e32 v206, 64, v205
	s_lshl_b32 s13, s12, 11
	s_lshl_b32 s12, s12, 12
	s_mov_b32 s30, 0xffff0000
	v_readlane_b32 s2, v253, 4
	v_readlane_b32 s3, v253, 5
	s_lshl_b32 s14, s20, 18
	s_add_u32 s2, s2, s14
	s_addc_u32 s3, s3, 0
	s_add_u32 s8, s50, 0xe629000
	s_addc_u32 s9, s51, 0
	s_add_u32 s8, s8, s14
	s_addc_u32 s9, s9, 0
	s_lshl_b32 s14, s21, 17
	s_add_u32 s4, s50, 0x5990000
	s_addc_u32 s5, s51, 0
	s_add_u32 s4, s4, s14
	s_addc_u32 s5, s5, 0
	s_lshl_b32 s14, s21, 15
	s_add_u32 s10, s50, 0x6190000
	s_addc_u32 s11, s51, 0
	s_add_u32 s10, s10, s14
	s_addc_u32 s11, s11, 0
	s_add_u32 m0, s12, 0x0
	s_nop 0
	global_load_lds_dwordx4 v192, s[2:3]
	s_add_u32 m0, s12, 0x400
	s_nop 0
	global_load_lds_dwordx4 v193, s[2:3]
	s_add_u32 m0, s12, 0x800
	s_nop 0
	global_load_lds_dwordx4 v194, s[2:3]
	s_add_u32 m0, s12, 0xc00
	s_nop 0
	global_load_lds_dwordx4 v195, s[2:3]
	s_add_u32 m0, s13, 0x4000
	s_nop 0
	global_load_lds_dwordx4 v196, s[4:5]
	s_add_u32 m0, s13, 0x4400
	s_nop 0
	global_load_lds_dwordx4 v197, s[4:5]
	s_add_u32 s2, s2, 0x80
	s_addc_u32 s3, s3, 0
	s_add_u32 s4, s4, 0x80
	s_addc_u32 s5, s5, 0
	v_mov_b32_e32 v0, 0
	v_mov_b32_e32 v1, 0
	v_mov_b32_e32 v2, 0
	v_mov_b32_e32 v3, 0
	v_mov_b32_e32 v4, 0
	v_mov_b32_e32 v5, 0
	v_mov_b32_e32 v6, 0
	v_mov_b32_e32 v7, 0
	v_mov_b32_e32 v8, 0
	v_mov_b32_e32 v9, 0
	v_mov_b32_e32 v10, 0
	v_mov_b32_e32 v11, 0
	v_mov_b32_e32 v12, 0
	v_mov_b32_e32 v13, 0
	v_mov_b32_e32 v14, 0
	v_mov_b32_e32 v15, 0
	v_mov_b32_e32 v16, 0
	v_mov_b32_e32 v17, 0
	v_mov_b32_e32 v18, 0
	v_mov_b32_e32 v19, 0
	v_mov_b32_e32 v20, 0
	v_mov_b32_e32 v21, 0
	v_mov_b32_e32 v22, 0
	v_mov_b32_e32 v23, 0
	v_mov_b32_e32 v24, 0
	v_mov_b32_e32 v25, 0
	v_mov_b32_e32 v26, 0
	v_mov_b32_e32 v27, 0
	v_mov_b32_e32 v28, 0
	v_mov_b32_e32 v29, 0
	v_mov_b32_e32 v30, 0
	v_mov_b32_e32 v31, 0
	v_mov_b32_e32 v32, 0
	v_mov_b32_e32 v33, 0
	v_mov_b32_e32 v34, 0
	v_mov_b32_e32 v35, 0
	v_mov_b32_e32 v36, 0
	v_mov_b32_e32 v37, 0
	v_mov_b32_e32 v38, 0
	v_mov_b32_e32 v39, 0
	v_mov_b32_e32 v40, 0
	v_mov_b32_e32 v41, 0
	v_mov_b32_e32 v42, 0
	v_mov_b32_e32 v43, 0
	v_mov_b32_e32 v44, 0
	v_mov_b32_e32 v45, 0
	v_mov_b32_e32 v46, 0
	v_mov_b32_e32 v47, 0
	v_mov_b32_e32 v48, 0
	v_mov_b32_e32 v49, 0
	v_mov_b32_e32 v50, 0
	v_mov_b32_e32 v51, 0
	v_mov_b32_e32 v52, 0
	v_mov_b32_e32 v53, 0
	v_mov_b32_e32 v54, 0
	v_mov_b32_e32 v55, 0
	v_mov_b32_e32 v56, 0
	v_mov_b32_e32 v57, 0
	v_mov_b32_e32 v58, 0
	v_mov_b32_e32 v59, 0
	v_mov_b32_e32 v60, 0
	v_mov_b32_e32 v61, 0
	v_mov_b32_e32 v62, 0
	v_mov_b32_e32 v63, 0
	s_waitcnt vmcnt(0)
	s_barrier
	s_add_u32 m0, s12, 0x6000
	ds_read_b128 v[96:99], v203 offset:0
	global_load_lds_dwordx4 v192, s[2:3]
	s_add_u32 m0, s12, 0x6400
	ds_read_b128 v[100:103], v203 offset:2048
	global_load_lds_dwordx4 v193, s[2:3]
	s_add_u32 m0, s12, 0x6800
	ds_read_b128 v[104:107], v203 offset:4096
	global_load_lds_dwordx4 v194, s[2:3]
	s_add_u32 m0, s12, 0x6c00
	ds_read_b128 v[108:111], v203 offset:6144
	global_load_lds_dwordx4 v195, s[2:3]
	s_add_u32 m0, s13, 0xa000
	ds_read_b128 v[128:131], v205 offset:16384
	global_load_lds_dwordx4 v196, s[4:5]
	s_add_u32 m0, s13, 0xa400
	ds_read_b128 v[132:135], v205 offset:18432
	global_load_lds_dwordx4 v197, s[4:5]
	s_add_u32 s2, s2, 0x80
	s_addc_u32 s3, s3, 0
	s_add_u32 s4, s4, 0x80
	s_addc_u32 s5, s5, 0
	ds_read_b128 v[112:115], v204 offset:0
	ds_read_b128 v[116:119], v204 offset:2048
	ds_read_b128 v[120:123], v204 offset:4096
	ds_read_b128 v[124:127], v204 offset:6144
	ds_read_b128 v[136:139], v206 offset:16384
	ds_read_b128 v[140:143], v206 offset:18432
	s_waitcnt lgkmcnt(0)
	s_mov_b32 s17, 0

.Lpr_skip4:
	v_readlane_b32 s12, v255, 2
	v_readlane_b32 s13, v255, 0
	v_and_b32_e32 v128, 63, v216
	v_lshrrev_b32_e32 v129, 6, v216
	v_lshrrev_b32_e32 v130, 3, v128
	v_and_b32_e32 v131, 7, v128
	v_readfirstlane_b32 s10, v129
	v_lshrrev_b32_e32 v132, 1, v130
	v_lshrrev_b32_e32 v133, 2, v130
	v_xor_b32_e32 v134, v132, v133
	v_xor_b32_e32 v135, 5, v134
	v_xor_b32_e32 v134, v131, v134
	v_xor_b32_e32 v135, v131, v135
	v_lshlrev_b32_e32 v134, 4, v134
	v_lshlrev_b32_e32 v135, 4, v135
	v_lshl_add_u32 v136, v129, 5, v130
	v_mul_u32_u24_e32 v137, 0x800, v136
	v_add_u32_e32 v192, v137, v134
	v_add_u32_e32 v193, v137, v135
	v_add_u32_e32 v193, 0x4000, v193
	v_add_u32_e32 v194, 0x8000, v192
	v_add_u32_e32 v195, 0x8000, v193
	v_and_b32_e32 v138, 15, v128
	v_lshrrev_b32_e32 v139, 4, v128
	v_lshrrev_b32_e32 v140, 1, v138
	v_lshrrev_b32_e32 v141, 2, v138
	v_lshrrev_b32_e32 v142, 3, v138
	v_xor_b32_e32 v141, v141, v142
	v_and_b32_e32 v141, 1, v141
	v_xor_b32_e32 v140, v140, v141
	v_xor_b32_e32 v140, v139, v140
	v_lshlrev_b32_e32 v140, 4, v140
	v_lshl_add_u32 v140, v138, 7, v140
	v_lshrrev_b32_e32 v141, 1, v129
	v_and_b32_e32 v142, 1, v129
	v_lshl_add_u32 v196, v141, 13, v140
	v_xor_b32_e32 v197, 64, v196
	v_lshl_add_u32 v198, v142, 13, v140
	v_xor_b32_e32 v199, 64, v198
	s_lshl_b32 s10, s10, 12
	s_lshl_b32 s5, s12, 18
	s_add_u32 s2, s28, s5
	s_addc_u32 s3, s29, 0
	s_lshl_b32 s5, s13, 18
	s_add_u32 s8, s14, s5
	s_addc_u32 s9, s15, 0
	s_add_u32 m0, s10, 0x0
	s_nop 0
	global_load_lds_dwordx4 v192, s[2:3]
	s_add_u32 m0, s10, 0x400
	s_nop 0
	global_load_lds_dwordx4 v193, s[2:3]
	s_add_u32 m0, s10, 0x800
	s_nop 0
	global_load_lds_dwordx4 v194, s[2:3]
	s_add_u32 m0, s10, 0xc00
	s_nop 0
	global_load_lds_dwordx4 v195, s[2:3]
	s_add_u32 m0, s10, 0x4000
	s_nop 0
	global_load_lds_dwordx4 v192, s[8:9]
	s_add_u32 m0, s10, 0x4400
	s_nop 0
	global_load_lds_dwordx4 v193, s[8:9]
	s_add_u32 m0, s10, 0x4800
	s_nop 0
	global_load_lds_dwordx4 v194, s[8:9]
	s_add_u32 m0, s10, 0x4c00
	s_nop 0
	global_load_lds_dwordx4 v195, s[8:9]
	s_add_u32 s2, s2, 0x80
	s_addc_u32 s3, s3, 0
	s_add_u32 s8, s8, 0x80
	s_addc_u32 s9, s9, 0
	v_mov_b32_e32 v0, 0
	v_mov_b32_e32 v1, 0
	v_mov_b32_e32 v2, 0
	v_mov_b32_e32 v3, 0
	v_mov_b32_e32 v4, 0
	v_mov_b32_e32 v5, 0
	v_mov_b32_e32 v6, 0
	v_mov_b32_e32 v7, 0
	v_mov_b32_e32 v8, 0
	v_mov_b32_e32 v9, 0
	v_mov_b32_e32 v10, 0
	v_mov_b32_e32 v11, 0
	v_mov_b32_e32 v12, 0
	v_mov_b32_e32 v13, 0
	v_mov_b32_e32 v14, 0
	v_mov_b32_e32 v15, 0
	v_mov_b32_e32 v16, 0
	v_mov_b32_e32 v17, 0
	v_mov_b32_e32 v18, 0
	v_mov_b32_e32 v19, 0
	v_mov_b32_e32 v20, 0
	v_mov_b32_e32 v21, 0
	v_mov_b32_e32 v22, 0
	v_mov_b32_e32 v23, 0
	v_mov_b32_e32 v24, 0
	v_mov_b32_e32 v25, 0
	v_mov_b32_e32 v26, 0
	v_mov_b32_e32 v27, 0
	v_mov_b32_e32 v28, 0
	v_mov_b32_e32 v29, 0
	v_mov_b32_e32 v30, 0
	v_mov_b32_e32 v31, 0
	v_mov_b32_e32 v32, 0
	v_mov_b32_e32 v33, 0
	v_mov_b32_e32 v34, 0
	v_mov_b32_e32 v35, 0
	v_mov_b32_e32 v36, 0
	v_mov_b32_e32 v37, 0
	v_mov_b32_e32 v38, 0
	v_mov_b32_e32 v39, 0
	v_mov_b32_e32 v40, 0
	v_mov_b32_e32 v41, 0
	v_mov_b32_e32 v42, 0
	v_mov_b32_e32 v43, 0
	v_mov_b32_e32 v44, 0
	v_mov_b32_e32 v45, 0
	v_mov_b32_e32 v46, 0
	v_mov_b32_e32 v47, 0
	v_mov_b32_e32 v48, 0
	v_mov_b32_e32 v49, 0
	v_mov_b32_e32 v50, 0
	v_mov_b32_e32 v51, 0
	v_mov_b32_e32 v52, 0
	v_mov_b32_e32 v53, 0
	v_mov_b32_e32 v54, 0
	v_mov_b32_e32 v55, 0
	v_mov_b32_e32 v56, 0
	v_mov_b32_e32 v57, 0
	v_mov_b32_e32 v58, 0
	v_mov_b32_e32 v59, 0
	v_mov_b32_e32 v60, 0
	v_mov_b32_e32 v61, 0
	v_mov_b32_e32 v62, 0
	v_mov_b32_e32 v63, 0
	s_waitcnt vmcnt(0)
	s_barrier
	s_add_u32 m0, s10, 0x8000
	ds_read_b128 v[64:67], v196 offset:0
	global_load_lds_dwordx4 v192, s[2:3]
	s_add_u32 m0, s10, 0x8400
	ds_read_b128 v[68:71], v196 offset:2048
	global_load_lds_dwordx4 v193, s[2:3]
	s_add_u32 m0, s10, 0x8800
	ds_read_b128 v[72:75], v196 offset:4096
	global_load_lds_dwordx4 v194, s[2:3]
	s_add_u32 m0, s10, 0x8c00
	ds_read_b128 v[76:79], v196 offset:6144
	global_load_lds_dwordx4 v195, s[2:3]
	s_add_u32 m0, s10, 0xc000
	ds_read_b128 v[96:99], v198 offset:16384
	global_load_lds_dwordx4 v192, s[8:9]
	s_add_u32 m0, s10, 0xc400
	ds_read_b128 v[100:103], v198 offset:18432
	global_load_lds_dwordx4 v193, s[8:9]
	s_add_u32 m0, s10, 0xc800
	ds_read_b128 v[104:107], v198 offset:20480
	global_load_lds_dwordx4 v194, s[8:9]
	s_add_u32 m0, s10, 0xcc00
	ds_read_b128 v[108:111], v198 offset:22528
	global_load_lds_dwordx4 v195, s[8:9]
	s_add_u32 s2, s2, 0x80
	s_addc_u32 s3, s3, 0
	s_add_u32 s8, s8, 0x80
	s_addc_u32 s9, s9, 0
	ds_read_b128 v[80:83], v197 offset:0
	ds_read_b128 v[84:87], v197 offset:2048
	ds_read_b128 v[88:91], v197 offset:4096
	ds_read_b128 v[92:95], v197 offset:6144
	ds_read_b128 v[112:115], v199 offset:16384
	ds_read_b128 v[116:119], v199 offset:18432
	ds_read_b128 v[120:123], v199 offset:20480
	ds_read_b128 v[124:127], v199 offset:22528
	s_waitcnt lgkmcnt(0)
	s_mov_b32 s11, 7

.Lpr_skip5:
	v_readlane_b32 s11, v254, 62
	v_readlane_b32 s12, v254, 60
	v_readlane_b32 s2, v253, 4
	v_readlane_b32 s3, v253, 5
	s_lshl_b32 s13, s11, 18
	s_add_u32 s2, s2, s13
	s_addc_u32 s3, s3, 0
	s_lshl_b32 s13, s12, 19
	s_add_u32 s4, s50, 0x65d0000
	s_addc_u32 s5, s51, 0
	s_add_u32 s4, s4, s13
	s_addc_u32 s5, s5, 0
	v_and_b32_e32 v152, 63, v216
	v_lshrrev_b32_e32 v153, 6, v216
	v_lshrrev_b32_e32 v154, 2, v152
	v_and_b32_e32 v155, 3, v152
	v_readfirstlane_b32 s11, v153
	v_lshrrev_b32_e32 v156, 3, v154
	v_mul_u32_u24_e32 v156, 3, v156
	v_xor_b32_e32 v156, v155, v156
	v_lshlrev_b32_e32 v156, 4, v156
	v_lshl_add_u32 v157, v153, 5, v154
	v_lshl_add_u32 v203, v157, 11, v156
	v_add_u32_e32 v204, 0x8000, v203
	v_lshl_add_u32 v157, v153, 6, v154
	v_lshlrev_b32_e32 v163, 4, v152
	v_lshl_add_u32 v205, v153, 12, v163
	v_add_u32_e32 v206, 0x400, v205
	v_add_u32_e32 v207, 0x800, v205
	v_add_u32_e32 v208, 0xc00, v205
	v_and_b32_e32 v158, 15, v152
	v_lshrrev_b32_e32 v159, 4, v152
	v_lshrrev_b32_e32 v160, 3, v158
	v_mul_u32_u24_e32 v160, 3, v160
	v_xor_b32_e32 v160, v159, v160
	v_lshlrev_b32_e32 v160, 4, v160
	v_lshl_add_u32 v160, v158, 6, v160
	v_lshrrev_b32_e32 v161, 1, v153
	v_and_b32_e32 v162, 1, v153
	v_lshl_add_u32 v209, v161, 12, v160
	v_lshl_add_u32 v210, v162, 13, v160
	s_lshl_b32 s12, s11, 12
	s_lshl_b32 s11, s11, 11
	s_barrier
	s_add_u32 m0, s11, 0x0
	s_nop 0
	global_load_lds_dwordx4 v203, s[2:3]
	s_add_u32 m0, s11, 0x400
	s_nop 0
	global_load_lds_dwordx4 v204, s[2:3]
	s_add_u32 m0, s12, 0x2000
	s_nop 0
	global_load_lds_dwordx4 v205, s[4:5]
	s_add_u32 m0, s12, 0x2400
	s_nop 0
	global_load_lds_dwordx4 v206, s[4:5]
	s_add_u32 m0, s12, 0x2800
	s_nop 0
	global_load_lds_dwordx4 v207, s[4:5]
	s_add_u32 m0, s12, 0x2c00
	s_nop 0
	global_load_lds_dwordx4 v208, s[4:5]
	s_add_u32 s2, s2, 0x40
	s_addc_u32 s3, s3, 0
	s_add_u32 s4, s4, 0x4000
	s_addc_u32 s5, s5, 0
	s_add_u32 m0, s11, 0x6000
	s_nop 0
	global_load_lds_dwordx4 v203, s[2:3]
	s_add_u32 m0, s11, 0x6400
	s_nop 0
	global_load_lds_dwordx4 v204, s[2:3]
	s_add_u32 m0, s12, 0x8000
	s_nop 0
	global_load_lds_dwordx4 v205, s[4:5]
	s_add_u32 m0, s12, 0x8400
	s_nop 0
	global_load_lds_dwordx4 v206, s[4:5]
	s_add_u32 m0, s12, 0x8800
	s_nop 0
	global_load_lds_dwordx4 v207, s[4:5]
	s_add_u32 m0, s12, 0x8c00
	s_nop 0
	global_load_lds_dwordx4 v208, s[4:5]
	s_add_u32 s2, s2, 0x40
	s_addc_u32 s3, s3, 0
	s_add_u32 s4, s4, 0x4000
	s_addc_u32 s5, s5, 0
	v_mov_b32_e32 v172, 0
	v_mov_b32_e32 v173, 0
	v_mov_b32_e32 v174, 0
	v_mov_b32_e32 v175, 0
	v_mov_b32_e32 v168, 0
	v_mov_b32_e32 v169, 0
	v_mov_b32_e32 v170, 0
	v_mov_b32_e32 v171, 0
	v_mov_b32_e32 v116, 0
	v_mov_b32_e32 v117, 0
	v_mov_b32_e32 v118, 0
	v_mov_b32_e32 v119, 0
	v_mov_b32_e32 v112, 0
	v_mov_b32_e32 v113, 0
	v_mov_b32_e32 v114, 0
	v_mov_b32_e32 v115, 0
	v_mov_b32_e32 v108, 0
	v_mov_b32_e32 v109, 0
	v_mov_b32_e32 v110, 0
	v_mov_b32_e32 v111, 0
	v_mov_b32_e32 v104, 0
	v_mov_b32_e32 v105, 0
	v_mov_b32_e32 v106, 0
	v_mov_b32_e32 v107, 0
	v_mov_b32_e32 v100, 0
	v_mov_b32_e32 v101, 0
	v_mov_b32_e32 v102, 0
	v_mov_b32_e32 v103, 0
	v_mov_b32_e32 v96, 0
	v_mov_b32_e32 v97, 0
	v_mov_b32_e32 v98, 0
	v_mov_b32_e32 v99, 0
	v_mov_b32_e32 v92, 0
	v_mov_b32_e32 v93, 0
	v_mov_b32_e32 v94, 0
	v_mov_b32_e32 v95, 0
	v_mov_b32_e32 v88, 0
	v_mov_b32_e32 v89, 0
	v_mov_b32_e32 v90, 0
	v_mov_b32_e32 v91, 0
	v_mov_b32_e32 v84, 0
	v_mov_b32_e32 v85, 0
	v_mov_b32_e32 v86, 0
	v_mov_b32_e32 v87, 0
	v_mov_b32_e32 v80, 0
	v_mov_b32_e32 v81, 0
	v_mov_b32_e32 v82, 0
	v_mov_b32_e32 v83, 0
	v_mov_b32_e32 v76, 0
	v_mov_b32_e32 v77, 0
	v_mov_b32_e32 v78, 0
	v_mov_b32_e32 v79, 0
	v_mov_b32_e32 v72, 0
	v_mov_b32_e32 v73, 0
	v_mov_b32_e32 v74, 0
	v_mov_b32_e32 v75, 0
	v_mov_b32_e32 v68, 0
	v_mov_b32_e32 v69, 0
	v_mov_b32_e32 v70, 0
	v_mov_b32_e32 v71, 0
	v_mov_b32_e32 v64, 0
	v_mov_b32_e32 v65, 0
	v_mov_b32_e32 v66, 0
	v_mov_b32_e32 v67, 0
	v_mov_b32_e32 v60, 0
	v_mov_b32_e32 v61, 0
	v_mov_b32_e32 v62, 0
	v_mov_b32_e32 v63, 0
	v_mov_b32_e32 v56, 0
	v_mov_b32_e32 v57, 0
	v_mov_b32_e32 v58, 0
	v_mov_b32_e32 v59, 0
	v_mov_b32_e32 v52, 0
	v_mov_b32_e32 v53, 0
	v_mov_b32_e32 v54, 0
	v_mov_b32_e32 v55, 0
	v_mov_b32_e32 v48, 0
	v_mov_b32_e32 v49, 0
	v_mov_b32_e32 v50, 0
	v_mov_b32_e32 v51, 0
	v_mov_b32_e32 v44, 0
	v_mov_b32_e32 v45, 0
	v_mov_b32_e32 v46, 0
	v_mov_b32_e32 v47, 0
	v_mov_b32_e32 v40, 0
	v_mov_b32_e32 v41, 0
	v_mov_b32_e32 v42, 0
	v_mov_b32_e32 v43, 0
	v_mov_b32_e32 v36, 0
	v_mov_b32_e32 v37, 0
	v_mov_b32_e32 v38, 0
	v_mov_b32_e32 v39, 0
	v_mov_b32_e32 v32, 0
	v_mov_b32_e32 v33, 0
	v_mov_b32_e32 v34, 0
	v_mov_b32_e32 v35, 0
	v_mov_b32_e32 v28, 0
	v_mov_b32_e32 v29, 0
	v_mov_b32_e32 v30, 0
	v_mov_b32_e32 v31, 0
	v_mov_b32_e32 v24, 0
	v_mov_b32_e32 v25, 0
	v_mov_b32_e32 v26, 0
	v_mov_b32_e32 v27, 0
	v_mov_b32_e32 v20, 0
	v_mov_b32_e32 v21, 0
	v_mov_b32_e32 v22, 0
	v_mov_b32_e32 v23, 0
	v_mov_b32_e32 v16, 0
	v_mov_b32_e32 v17, 0
	v_mov_b32_e32 v18, 0
	v_mov_b32_e32 v19, 0
	v_mov_b32_e32 v12, 0
	v_mov_b32_e32 v13, 0
	v_mov_b32_e32 v14, 0
	v_mov_b32_e32 v15, 0
	v_mov_b32_e32 v8, 0
	v_mov_b32_e32 v9, 0
	v_mov_b32_e32 v10, 0
	v_mov_b32_e32 v11, 0
	v_mov_b32_e32 v4, 0
	v_mov_b32_e32 v5, 0
	v_mov_b32_e32 v6, 0
	v_mov_b32_e32 v7, 0
	v_mov_b32_e32 v0, 0
	v_mov_b32_e32 v1, 0
	v_mov_b32_e32 v2, 0
	v_mov_b32_e32 v3, 0
	s_waitcnt vmcnt(6)
	s_barrier
	ds_read_b128 v[120:123], v209 offset:0
	ds_read_b128 v[124:127], v209 offset:1024
	ds_read_b128 v[128:131], v209 offset:2048
	ds_read_b128 v[132:135], v209 offset:3072
	ds_read_b128 v[152:155], v210 offset:8192
	ds_read_b128 v[156:159], v210 offset:9216
	ds_read_b128 v[160:163], v210 offset:10240
	ds_read_b128 v[164:167], v210 offset:11264
	ds_read_b128 v[176:179], v210 offset:12288
	ds_read_b128 v[180:183], v210 offset:13312
	s_add_u32 m0, s11, 0xc000
	s_nop 0
	global_load_lds_dwordx4 v203, s[2:3]
	s_add_u32 m0, s11, 0xc400
	s_nop 0
	global_load_lds_dwordx4 v204, s[2:3]
	s_add_u32 m0, s12, 0xe000
	s_nop 0
	global_load_lds_dwordx4 v205, s[4:5]
	s_add_u32 m0, s12, 0xe400
	s_nop 0
	global_load_lds_dwordx4 v206, s[4:5]
	s_add_u32 m0, s12, 0xe800
	s_nop 0
	global_load_lds_dwordx4 v207, s[4:5]
	s_add_u32 m0, s12, 0xec00
	s_nop 0
	global_load_lds_dwordx4 v208, s[4:5]
	s_add_u32 s2, s2, 0x40
	s_addc_u32 s3, s3, 0
	s_add_u32 s4, s4, 0x4000
	s_addc_u32 s5, s5, 0
	ds_read_b128 v[184:187], v210 offset:14336
	ds_read_b128 v[188:191], v210 offset:15360
	s_waitcnt lgkmcnt(7)
	v_mfma_f32_16x16x32_bf16 v[172:175], v[152:155], v[120:123], v[172:175]
	v_mfma_f32_16x16x32_bf16 v[92:95], v[152:155], v[124:127], v[92:95]
	v_mfma_f32_16x16x32_bf16 v[60:63], v[152:155], v[128:131], v[60:63]
	v_mfma_f32_16x16x32_bf16 v[28:31], v[152:155], v[132:135], v[28:31]
	s_waitcnt lgkmcnt(6)
	v_mfma_f32_16x16x32_bf16 v[168:171], v[156:159], v[120:123], v[168:171]
	v_mfma_f32_16x16x32_bf16 v[88:91], v[156:159], v[124:127], v[88:91]
	v_mfma_f32_16x16x32_bf16 v[56:59], v[156:159], v[128:131], v[56:59]
	v_mfma_f32_16x16x32_bf16 v[24:27], v[156:159], v[132:135], v[24:27]
	s_waitcnt lgkmcnt(5)
	v_mfma_f32_16x16x32_bf16 v[116:119], v[160:163], v[120:123], v[116:119]
	v_mfma_f32_16x16x32_bf16 v[84:87], v[160:163], v[124:127], v[84:87]
	v_mfma_f32_16x16x32_bf16 v[52:55], v[160:163], v[128:131], v[52:55]
	v_mfma_f32_16x16x32_bf16 v[20:23], v[160:163], v[132:135], v[20:23]
	s_waitcnt lgkmcnt(4)
	v_mfma_f32_16x16x32_bf16 v[112:115], v[164:167], v[120:123], v[112:115]
	v_mfma_f32_16x16x32_bf16 v[80:83], v[164:167], v[124:127], v[80:83]
	v_mfma_f32_16x16x32_bf16 v[48:51], v[164:167], v[128:131], v[48:51]
	v_mfma_f32_16x16x32_bf16 v[16:19], v[164:167], v[132:135], v[16:19]
	s_waitcnt lgkmcnt(3)
	v_mfma_f32_16x16x32_bf16 v[108:111], v[176:179], v[120:123], v[108:111]
	v_mfma_f32_16x16x32_bf16 v[76:79], v[176:179], v[124:127], v[76:79]
	v_mfma_f32_16x16x32_bf16 v[44:47], v[176:179], v[128:131], v[44:47]
	v_mfma_f32_16x16x32_bf16 v[12:15], v[176:179], v[132:135], v[12:15]
	s_waitcnt lgkmcnt(2)
	v_mfma_f32_16x16x32_bf16 v[104:107], v[180:183], v[120:123], v[104:107]
	v_mfma_f32_16x16x32_bf16 v[72:75], v[180:183], v[124:127], v[72:75]
	v_mfma_f32_16x16x32_bf16 v[40:43], v[180:183], v[128:131], v[40:43]
	v_mfma_f32_16x16x32_bf16 v[8:11], v[180:183], v[132:135], v[8:11]
	s_waitcnt lgkmcnt(0)
	s_mov_b32 s13, 5

.Lpr_skip6:
	v_readlane_b32 s12, v255, 31
	v_readlane_b32 s13, v255, 32
	v_and_b32_e32 v128, 63, v216
	v_lshrrev_b32_e32 v129, 6, v216
	v_lshrrev_b32_e32 v130, 3, v128
	v_and_b32_e32 v131, 7, v128
	v_readfirstlane_b32 s10, v129
	v_lshrrev_b32_e32 v132, 1, v130
	v_lshrrev_b32_e32 v133, 2, v130
	v_xor_b32_e32 v134, v132, v133
	v_xor_b32_e32 v135, 5, v134
	v_xor_b32_e32 v134, v131, v134
	v_xor_b32_e32 v135, v131, v135
	v_lshlrev_b32_e32 v134, 4, v134
	v_lshlrev_b32_e32 v135, 4, v135
	v_lshl_add_u32 v136, v129, 5, v130
	v_mul_u32_u24_e32 v137, 0x1600, v136
	v_add_u32_e32 v192, v137, v134
	v_add_u32_e32 v193, v137, v135
	v_add_u32_e32 v193, 0xb000, v193
	v_add_u32_e32 v194, 0x16000, v192
	v_add_u32_e32 v195, 0x16000, v193
	v_and_b32_e32 v138, 15, v128
	v_lshrrev_b32_e32 v139, 4, v128
	v_lshrrev_b32_e32 v140, 1, v138
	v_lshrrev_b32_e32 v141, 2, v138
	v_lshrrev_b32_e32 v142, 3, v138
	v_xor_b32_e32 v141, v141, v142
	v_and_b32_e32 v141, 1, v141
	v_xor_b32_e32 v140, v140, v141
	v_xor_b32_e32 v140, v139, v140
	v_lshlrev_b32_e32 v140, 4, v140
	v_lshl_add_u32 v140, v138, 7, v140
	v_lshrrev_b32_e32 v141, 1, v129
	v_and_b32_e32 v142, 1, v129
	v_lshl_add_u32 v196, v141, 13, v140
	v_xor_b32_e32 v197, 64, v196
	v_lshl_add_u32 v198, v142, 13, v140
	v_xor_b32_e32 v199, 64, v198
	s_lshl_b32 s10, s10, 12
	s_mul_hi_u32 s11, s12, 0xb0000
	s_mul_i32 s5, s12, 0xb0000
	s_add_u32 s2, s28, s5
	s_addc_u32 s3, s29, s11
	v_readlane_b32 s8, v253, 23
	v_readlane_b32 s9, v253, 24
	s_mul_hi_u32 s11, s13, 0xb0000
	s_mul_i32 s5, s13, 0xb0000
	s_add_u32 s8, s8, s5
	s_addc_u32 s9, s9, s11
	s_add_u32 m0, s10, 0x0
	s_nop 0
	global_load_lds_dwordx4 v192, s[2:3]
	s_add_u32 m0, s10, 0x400
	s_nop 0
	global_load_lds_dwordx4 v193, s[2:3]
	s_add_u32 m0, s10, 0x800
	s_nop 0
	global_load_lds_dwordx4 v194, s[2:3]
	s_add_u32 m0, s10, 0xc00
	s_nop 0
	global_load_lds_dwordx4 v195, s[2:3]
	s_add_u32 m0, s10, 0x4000
	s_nop 0
	global_load_lds_dwordx4 v192, s[8:9]
	s_add_u32 m0, s10, 0x4400
	s_nop 0
	global_load_lds_dwordx4 v193, s[8:9]
	s_add_u32 m0, s10, 0x4800
	s_nop 0
	global_load_lds_dwordx4 v194, s[8:9]
	s_add_u32 m0, s10, 0x4c00
	s_nop 0
	global_load_lds_dwordx4 v195, s[8:9]
	s_add_u32 s2, s2, 0x80
	s_addc_u32 s3, s3, 0
	s_add_u32 s8, s8, 0x80
	s_addc_u32 s9, s9, 0
	v_mov_b32_e32 v0, 0
	v_mov_b32_e32 v1, 0
	v_mov_b32_e32 v2, 0
	v_mov_b32_e32 v3, 0
	v_mov_b32_e32 v4, 0
	v_mov_b32_e32 v5, 0
	v_mov_b32_e32 v6, 0
	v_mov_b32_e32 v7, 0
	v_mov_b32_e32 v8, 0
	v_mov_b32_e32 v9, 0
	v_mov_b32_e32 v10, 0
	v_mov_b32_e32 v11, 0
	v_mov_b32_e32 v12, 0
	v_mov_b32_e32 v13, 0
	v_mov_b32_e32 v14, 0
	v_mov_b32_e32 v15, 0
	v_mov_b32_e32 v16, 0
	v_mov_b32_e32 v17, 0
	v_mov_b32_e32 v18, 0
	v_mov_b32_e32 v19, 0
	v_mov_b32_e32 v20, 0
	v_mov_b32_e32 v21, 0
	v_mov_b32_e32 v22, 0
	v_mov_b32_e32 v23, 0
	v_mov_b32_e32 v24, 0
	v_mov_b32_e32 v25, 0
	v_mov_b32_e32 v26, 0
	v_mov_b32_e32 v27, 0
	v_mov_b32_e32 v28, 0
	v_mov_b32_e32 v29, 0
	v_mov_b32_e32 v30, 0
	v_mov_b32_e32 v31, 0
	v_mov_b32_e32 v32, 0
	v_mov_b32_e32 v33, 0
	v_mov_b32_e32 v34, 0
	v_mov_b32_e32 v35, 0
	v_mov_b32_e32 v36, 0
	v_mov_b32_e32 v37, 0
	v_mov_b32_e32 v38, 0
	v_mov_b32_e32 v39, 0
	v_mov_b32_e32 v40, 0
	v_mov_b32_e32 v41, 0
	v_mov_b32_e32 v42, 0
	v_mov_b32_e32 v43, 0
	v_mov_b32_e32 v44, 0
	v_mov_b32_e32 v45, 0
	v_mov_b32_e32 v46, 0
	v_mov_b32_e32 v47, 0
	v_mov_b32_e32 v48, 0
	v_mov_b32_e32 v49, 0
	v_mov_b32_e32 v50, 0
	v_mov_b32_e32 v51, 0
	v_mov_b32_e32 v52, 0
	v_mov_b32_e32 v53, 0
	v_mov_b32_e32 v54, 0
	v_mov_b32_e32 v55, 0
	v_mov_b32_e32 v56, 0
	v_mov_b32_e32 v57, 0
	v_mov_b32_e32 v58, 0
	v_mov_b32_e32 v59, 0
	v_mov_b32_e32 v60, 0
	v_mov_b32_e32 v61, 0
	v_mov_b32_e32 v62, 0
	v_mov_b32_e32 v63, 0
	s_waitcnt vmcnt(0)
	s_barrier
	s_add_u32 m0, s10, 0x8000
	ds_read_b128 v[64:67], v196 offset:0
	global_load_lds_dwordx4 v192, s[2:3]
	s_add_u32 m0, s10, 0x8400
	ds_read_b128 v[68:71], v196 offset:2048
	global_load_lds_dwordx4 v193, s[2:3]
	s_add_u32 m0, s10, 0x8800
	ds_read_b128 v[72:75], v196 offset:4096
	global_load_lds_dwordx4 v194, s[2:3]
	s_add_u32 m0, s10, 0x8c00
	ds_read_b128 v[76:79], v196 offset:6144
	global_load_lds_dwordx4 v195, s[2:3]
	s_add_u32 m0, s10, 0xc000
	ds_read_b128 v[96:99], v198 offset:16384
	global_load_lds_dwordx4 v192, s[8:9]
	s_add_u32 m0, s10, 0xc400
	ds_read_b128 v[100:103], v198 offset:18432
	global_load_lds_dwordx4 v193, s[8:9]
	s_add_u32 m0, s10, 0xc800
	ds_read_b128 v[104:107], v198 offset:20480
	global_load_lds_dwordx4 v194, s[8:9]
	s_add_u32 m0, s10, 0xcc00
	ds_read_b128 v[108:111], v198 offset:22528
	global_load_lds_dwordx4 v195, s[8:9]
	s_add_u32 s2, s2, 0x80
	s_addc_u32 s3, s3, 0
	s_add_u32 s8, s8, 0x80
	s_addc_u32 s9, s9, 0
	ds_read_b128 v[80:83], v197 offset:0
	ds_read_b128 v[84:87], v197 offset:2048
	ds_read_b128 v[88:91], v197 offset:4096
	ds_read_b128 v[92:95], v197 offset:6144
	ds_read_b128 v[112:115], v199 offset:16384
	ds_read_b128 v[116:119], v199 offset:18432
	ds_read_b128 v[120:123], v199 offset:20480
	ds_read_b128 v[124:127], v199 offset:22528
	s_waitcnt lgkmcnt(0)
	s_mov_b32 s11, 21
